# grid barrier P3->P4 replaced by a counter sync on the 128 scan workgroups (P4 no longer waits for P3's sample attention/GLA)
# baseline (speedup 1.0000x reference)
.LBB0_791:
	s_waitcnt vmcnt(0)
	s_barrier
	s_mov_b64 s[0:1], exec
	v_readlane_b32 s8, v245, 16
	v_readlane_b32 s9, v245, 17
	s_and_b64 s[8:9], s[0:1], s[8:9]
	s_mov_b64 exec, s[8:9]
	s_cbranch_execz .LBB0_843
	s_add_u32 s10, s62, 0x8000
	s_addc_u32 s11, s63, 0
	v_mov_b32_e32 v0, 0
	s_cmpk_gt_u32 s2, 0x7f
	s_cbranch_scc1 .Lb3_wait
	buffer_wbl2 sc1
	s_waitcnt vmcnt(0)
	v_mov_b32_e32 v1, 1
	global_atomic_add v0, v1, s[10:11]
.Lb3_wait:
	s_mov_b32 s20, 0
.Lb3_spin:
	global_load_dword v2, v0, s[10:11] sc1
	s_waitcnt vmcnt(0)
	v_readfirstlane_b32 s8, v2
	s_nop 3
	s_cmpk_ge_u32 s8, 0x80
	s_cbranch_scc1 .Lb3_done
	s_sleep 1
	s_add_i32 s20, s20, 1
	s_cmp_lt_u32 s20, 0x100000
	s_cbranch_scc1 .Lb3_spin
.Lb3_done:
	buffer_inv sc1
	s_waitcnt vmcnt(0)
